# v19: v18 + prompt-attention phase: odd workgroups run their two attention units before their HGRN output items (even ones after), so the memory-bound and the matrix-bound halves of the phase overlap a
# baseline (speedup 1.0000x reference)
.LBB0_1308:
	s_bitcmp1_b32 s94, 0
	s_cbranch_scc1 .Lattn_first
	s_cmpk_lt_i32 s94, 0x400
	s_cbranch_scc1 .LBB0_1310
.Lattn_first:
	v_mbcnt_hi_u32_b32 v211, -1, v216
	s_and_b32 s2, s87, 0xffffffc0
	s_waitcnt vmcnt(0)
	v_and_b32_e32 v0, 64, v211
	v_add_u32_e32 v21, 64, v0
	v_xor_b32_e32 v50, 1, v211
	v_xor_b32_e32 v51, 2, v211
	v_mov_b32_e32 v217, s2
	s_cbranch_execz .LBB0_1311
	s_branch .LBB0_1314

.LBB0_1312:
	s_mov_b64 s[22:23], s[4:5]
	s_mov_b64 s[18:19], s[64:65]
	s_mov_b64 s[20:21], s[2:3]
	s_mov_b64 s[28:29], s[6:7]
	s_mov_b64 s[24:25], s[8:9]
	s_mov_b64 s[30:31], s[0:1]
	s_ashr_i32 s26, s54, 9
	v_lshl_add_u64 v[2:3], s[28:29], 0, v[34:35]
	v_lshl_add_u64 v[2:3], v[2:3], 0, s[14:15]
	flat_load_dwordx4 v[16:19], v[2:3]
	v_readfirstlane_b32 s12, v52
	s_ashr_i32 s27, s26, 31
	s_ashr_i32 s55, s12, 3
	s_and_b32 s57, s38, 0xfc0
	s_lshl_b64 s[26:27], s[26:27], 12
	s_andn2_b32 s55, s55, 31
	v_lshl_add_u64 v[4:5], s[28:29], 0, v[32:33]
	v_lshl_add_u64 v[6:7], s[28:29], 0, v[30:31]
	v_lshl_add_u64 v[8:9], s[28:29], 0, v[28:29]
	s_or_b32 s26, s26, s57
	s_ashr_i32 s29, s55, 31
	v_mov_b64_e32 v[0:1], s[30:31]
	v_lshl_add_u64 v[46:47], v[4:5], 0, s[14:15]
	s_add_u32 s28, s26, s55
	v_lshl_add_u64 v[4:5], s[26:27], 0, v[26:27]
	s_addc_u32 s29, s27, s29
	v_mad_u64_u32 v[0:1], s[26:27], v4, s36, v[0:1]
	v_lshl_add_u64 v[44:45], v[6:7], 0, s[14:15]
	v_or_b32_e32 v6, s55, v54
	s_lshl_b64 s[26:27], s[28:29], 12
	v_lshl_add_u64 v[42:43], v[8:9], 0, s[14:15]
	v_mul_lo_u32 v8, v6, s37
	v_lshlrev_b64 v[6:7], 11, v[4:5]
	s_add_u32 s22, s22, s26
	v_or_b32_e32 v2, s28, v20
	v_mov_b32_e32 v3, s29
	v_mad_i32_i24 v1, v5, s36, v1
	v_lshl_add_u64 v[4:5], s[24:25], 0, v[6:7]
	s_addc_u32 s23, s23, s27
	s_and_b32 s24, s10, 0x380
	v_lshlrev_b64 v[2:3], 11, v[2:3]
	s_lshl_b32 s25, s24, 2
	v_lshl_add_u64 v[2:3], s[20:21], 0, v[2:3]
	s_add_u32 s20, s22, s25
	s_addc_u32 s21, s23, 0
	s_lshr_b32 s12, s12, 1
	s_and_b32 s12, s12, 0x60
	s_lshl_b32 s22, s12, 2
	s_add_u32 s20, s20, s22
	s_addc_u32 s21, s21, 0
	v_lshl_add_u32 v65, s12, 1, v53
	s_lshl_b32 s12, s24, 1
	v_lshl_add_u64 v[6:7], s[20:21], 0, v[36:37]
	v_lshl_add_u64 v[4:5], v[4:5], 0, s[12:13]
	v_lshl_add_u64 v[6:7], v[6:7], 0, v[24:25]
	v_lshl_add_u64 v[48:49], v[4:5], 0, v[40:41]
	v_add_co_u32_e32 v4, vcc, s33, v6
	v_add3_u32 v131, v55, s22, v8
	s_nop 0
	v_addc_co_u32_e32 v5, vcc, 0, v7, vcc
	v_add_co_u32_e32 v8, vcc, s34, v6
	v_lshl_add_u64 v[2:3], v[2:3], 0, s[12:13]
	s_nop 0
	v_addc_co_u32_e32 v9, vcc, 0, v7, vcc
	v_add_co_u32_e32 v10, vcc, s35, v6
	v_lshl_add_u64 v[0:1], v[0:1], 0, s[12:13]
	s_nop 0
	v_addc_co_u32_e32 v11, vcc, 0, v7, vcc
	v_add_co_u32_e32 v12, vcc, s41, v6
	s_add_u32 s18, s18, s25
	s_nop 0
	v_addc_co_u32_e32 v13, vcc, 0, v7, vcc
	v_add_co_u32_e32 v14, vcc, s42, v6
	v_lshl_add_u64 v[2:3], v[2:3], 0, v[38:39]
	s_nop 0
	v_addc_co_u32_e32 v15, vcc, 0, v7, vcc
	v_add_co_u32_e32 v106, vcc, s43, v6
	v_lshl_add_u64 v[0:1], v[0:1], 0, v[40:41]
	s_nop 0
	v_addc_co_u32_e32 v107, vcc, 0, v7, vcc
	v_add_co_u32_e32 v108, vcc, s44, v6
	s_addc_u32 s19, s19, 0
	s_nop 0
	v_addc_co_u32_e32 v109, vcc, 0, v7, vcc
	v_add_co_u32_e32 v110, vcc, s45, v6
	flat_load_dwordx4 v[66:69], v[2:3]
	flat_load_dwordx4 v[70:73], v[2:3] offset:32
	flat_load_dwordx4 v[74:77], v[2:3] offset:64
	flat_load_dwordx4 v[78:81], v[2:3] offset:96
	flat_load_dwordx4 v[82:85], v[2:3] offset:128
	flat_load_dwordx4 v[86:89], v[2:3] offset:160
	flat_load_dwordx4 v[90:93], v[2:3] offset:192
	flat_load_dwordx4 v[94:97], v[2:3] offset:224
	flat_load_dwordx4 v[98:101], v[0:1]
	flat_load_dwordx4 v[102:105], v[0:1] offset:16
	v_addc_co_u32_e32 v111, vcc, 0, v7, vcc
	v_add_co_u32_e32 v112, vcc, s46, v6
	v_lshl_add_u64 v[126:127], s[18:19], 0, v[22:23]
	s_nop 0
	v_addc_co_u32_e32 v113, vcc, 0, v7, vcc
	v_add_co_u32_e32 v114, vcc, s47, v6
	v_add_u32_e32 v130, 0xa000, v65
	s_nop 0
	v_addc_co_u32_e32 v115, vcc, 0, v7, vcc
	v_add_co_u32_e32 v116, vcc, s48, v6
	v_add_u32_e32 v132, 0x400, v131
	s_nop 0
	v_addc_co_u32_e32 v117, vcc, 0, v7, vcc
	v_add_co_u32_e32 v118, vcc, s49, v6
	v_add_u32_e32 v133, 0x1000, v131
	s_nop 0
	v_addc_co_u32_e32 v119, vcc, 0, v7, vcc
	v_add_co_u32_e32 v120, vcc, s50, v6
	v_add_u32_e32 v134, 0x1400, v131
	s_nop 0
	v_addc_co_u32_e32 v121, vcc, 0, v7, vcc
	v_add_co_u32_e32 v122, vcc, s51, v6
	v_add_u32_e32 v135, 0x2000, v131
	s_nop 0
	v_addc_co_u32_e32 v123, vcc, 0, v7, vcc
	v_add_co_u32_e32 v124, vcc, s52, v6
	v_add_u32_e32 v136, 0x2400, v131
	s_nop 0
	v_addc_co_u32_e32 v125, vcc, 0, v7, vcc
	flat_load_dword v0, v[6:7]
	flat_load_dword v1, v[4:5]
	flat_load_dword v2, v[8:9]
	flat_load_dword v3, v[10:11]
	s_nop 0
	flat_load_dword v4, v[12:13]
	flat_load_dword v5, v[14:15]
	flat_load_dword v6, v[106:107]
	flat_load_dword v7, v[108:109]
	flat_load_dword v8, v[110:111]
	flat_load_dword v9, v[112:113]
	flat_load_dword v10, v[114:115]
	flat_load_dword v11, v[116:117]
	flat_load_dword v12, v[118:119]
	flat_load_dword v13, v[120:121]
	flat_load_dword v14, v[122:123]
	flat_load_dword v15, v[124:125]
	flat_load_dwordx4 v[106:109], v[126:127]
	flat_load_dwordx4 v[110:113], v[126:127] offset:16
	flat_load_dwordx4 v[114:117], v[126:127] offset:32
	flat_load_dwordx4 v[118:121], v[126:127] offset:48
	flat_load_dwordx4 v[240:243], v[46:47]
	flat_load_dwordx4 v[244:247], v[44:45]
	flat_load_dwordx4 v[248:251], v[42:43]
	s_waitcnt vmcnt(0) lgkmcnt(0)
	ds_write_b128 v60, v[16:19] offset:40960
	ds_write_b128 v61, v[240:243] offset:40960
	ds_write_b128 v62, v[244:247] offset:40960
	ds_write_b128 v63, v[248:251] offset:40960
	v_add_u32_e32 v137, 0x3000, v131
	v_add_u32_e32 v138, 0x3400, v131
	s_add_i32 s54, s54, s92
	s_add_i32 s38, s38, s39
	s_add_i32 s10, s10, s40
	s_add_u32 s14, s14, s16
	s_addc_u32 s15, s15, s17
	s_cmpk_gt_i32 s54, 0x3ff
	v_and_b32_e32 v125, 0xffff0000, v101
	v_and_b32_e32 v47, 0xffff0000, v104
	v_lshlrev_b32_e32 v46, 16, v104
	v_and_b32_e32 v129, 0xffff0000, v105
	v_lshlrev_b32_e32 v128, 16, v105
	v_lshlrev_b32_e32 v124, 16, v101
	v_and_b32_e32 v101, 0xffff0000, v100
	v_lshlrev_b32_e32 v100, 16, v100
	v_and_b32_e32 v127, 0xffff0000, v99
	v_lshlrev_b32_e32 v126, 16, v99
	v_and_b32_e32 v99, 0xffff0000, v98
	v_lshlrev_b32_e32 v98, 16, v98
	v_and_b32_e32 v123, 0xffff0000, v103
	v_lshlrev_b32_e32 v122, 16, v103
	v_and_b32_e32 v103, 0xffff0000, v102
	v_lshlrev_b32_e32 v102, 16, v102
	s_waitcnt vmcnt(0) lgkmcnt(0)
	s_barrier
	ds_read_u16 v16, v65 offset:40960
	ds_read_u16 v17, v65 offset:41232
	ds_read_u16 v18, v65 offset:41504
	ds_read_u16 v19, v65 offset:41776
	ds_read_u16 v42, v65 offset:42048
	ds_read_u16 v43, v65 offset:42320
	ds_read_u16 v44, v65 offset:42592
	ds_read_u16 v45, v65 offset:42864
	ds_read_u16 v104, v65 offset:45312
	ds_read_u16 v105, v65 offset:45584
	ds_read_u16 v139, v65 offset:45856
	ds_read_u16 v140, v65 offset:46128
	ds_read_u16 v141, v65 offset:46400
	ds_read_u16 v142, v65 offset:46672
	ds_read_u16 v143, v65 offset:46944
	ds_read_u16 v144, v65 offset:47216
	ds_read_u16 v145, v65 offset:49664
	ds_read_u16 v146, v65 offset:49936
	ds_read_u16 v147, v65 offset:50208
	ds_read_u16 v148, v65 offset:50480
	ds_read_u16 v149, v65 offset:50752
	ds_read_u16 v150, v65 offset:51024
	ds_read_u16 v151, v65 offset:51296
	ds_read_u16 v152, v65 offset:51568
	ds_read_u16 v153, v65 offset:54016
	ds_read_u16 v154, v65 offset:54288
	ds_read_u16 v155, v65 offset:54560
	ds_read_u16 v156, v65 offset:54832
	ds_read_u16 v157, v65 offset:55104
	ds_read_u16 v158, v65 offset:55376
	ds_read_u16 v159, v65 offset:55648
	ds_read_u16 v160, v65 offset:55920
	ds_read_u16 v161, v65 offset:58368
	ds_read_u16 v162, v65 offset:58640
	ds_read_u16 v163, v65 offset:58912
	ds_read_u16 v164, v65 offset:59184
	ds_read_u16 v165, v65 offset:59456
	ds_read_u16 v166, v65 offset:59728
	ds_read_u16 v167, v65 offset:60000
	ds_read_u16 v168, v65 offset:60272
	ds_read_u16 v169, v65 offset:62720
	ds_read_u16 v170, v65 offset:62992
	ds_read_u16 v171, v65 offset:63264
	ds_read_u16 v172, v65 offset:63536
	s_waitcnt lgkmcnt(14)
	v_lshl_or_b32 v16, v17, 16, v16
	v_lshl_or_b32 v17, v19, 16, v18
	v_lshl_or_b32 v18, v43, 16, v42
	v_lshl_or_b32 v19, v45, 16, v44
	ds_read_u16 v42, v65 offset:63808
	ds_read_u16 v43, v65 offset:64080
	ds_read_u16 v44, v65 offset:64352
	v_mfma_f32_32x32x16_bf16 v[0:15], v[66:69], v[16:19], v[0:15]
	v_lshl_or_b32 v16, v105, 16, v104
	v_lshl_or_b32 v17, v140, 16, v139
	v_lshl_or_b32 v18, v142, 16, v141
	v_lshl_or_b32 v19, v144, 16, v143
	ds_read_u16 v45, v65 offset:64624
	ds_read_u16 v65, v130 offset:26112
	ds_read_u16 v66, v130 offset:26384
	ds_read_u16 v67, v130 offset:26656
	ds_read_u16 v68, v130 offset:26928
	ds_read_u16 v69, v130 offset:27200
	v_mfma_f32_32x32x16_bf16 v[0:15], v[70:73], v[16:19], v[0:15]
	v_lshl_or_b32 v16, v146, 16, v145
	v_lshl_or_b32 v17, v148, 16, v147
	v_lshl_or_b32 v18, v150, 16, v149
	v_lshl_or_b32 v19, v152, 16, v151
	ds_read_u16 v70, v130 offset:27472
	ds_read_u16 v71, v130 offset:27744
	ds_read_u16 v72, v130 offset:28016
	v_mfma_f32_32x32x16_bf16 v[0:15], v[74:77], v[16:19], v[0:15]
	v_lshl_or_b32 v16, v154, 16, v153
	v_lshl_or_b32 v17, v156, 16, v155
	v_lshl_or_b32 v18, v158, 16, v157
	s_waitcnt lgkmcnt(14)
	v_lshl_or_b32 v19, v160, 16, v159
	ds_read_u16 v73, v130 offset:30464
	ds_read_u16 v74, v130 offset:30736
	ds_read_u16 v75, v130 offset:31008
	v_mfma_f32_32x32x16_bf16 v[0:15], v[78:81], v[16:19], v[0:15]
	v_lshl_or_b32 v16, v162, 16, v161
	v_lshl_or_b32 v17, v164, 16, v163
	v_lshl_or_b32 v18, v166, 16, v165
	v_lshl_or_b32 v19, v168, 16, v167
	s_nop 1
	v_mfma_f32_32x32x16_bf16 v[0:15], v[82:85], v[16:19], v[0:15]
	v_lshl_or_b32 v16, v170, 16, v169
	s_waitcnt lgkmcnt(14)
	v_lshl_or_b32 v17, v172, 16, v171
	s_waitcnt lgkmcnt(13)
	v_lshl_or_b32 v18, v43, 16, v42
	s_waitcnt lgkmcnt(11)
	v_lshl_or_b32 v19, v45, 16, v44
	ds_read_u16 v42, v130 offset:31280
	ds_read_u16 v43, v130 offset:31552
	ds_read_u16 v44, v130 offset:31824
	v_mfma_f32_32x32x16_bf16 v[0:15], v[86:89], v[16:19], v[0:15]
	s_waitcnt lgkmcnt(12)
	v_lshl_or_b32 v16, v66, 16, v65
	s_waitcnt lgkmcnt(10)
	v_lshl_or_b32 v17, v68, 16, v67
	s_waitcnt lgkmcnt(8)
	v_lshl_or_b32 v18, v70, 16, v69
	s_waitcnt lgkmcnt(6)
	v_lshl_or_b32 v19, v72, 16, v71
	s_nop 1
	v_mfma_f32_32x32x16_bf16 v[0:15], v[90:93], v[16:19], v[0:15]
	ds_read_u16 v19, v130 offset:32096
	ds_read_u16 v45, v130 offset:32368
	s_waitcnt lgkmcnt(6)
	v_lshl_or_b32 v16, v74, 16, v73
	s_waitcnt lgkmcnt(4)
	v_lshl_or_b32 v17, v42, 16, v75
	s_waitcnt lgkmcnt(2)
	v_lshl_or_b32 v18, v44, 16, v43
	s_waitcnt lgkmcnt(0)
	v_lshl_or_b32 v19, v45, 16, v19
	s_nop 1
	v_mfma_f32_32x32x16_bf16 v[0:15], v[94:97], v[16:19], v[0:15]
	s_nop 11
	ds_write2_b32 v131, v0, v1 offset1:132
	ds_write2_b32 v132, v2, v3 offset0:8 offset1:140
	ds_write2_b32 v133, v4, v5 offset0:32 offset1:164
	ds_write2_b32 v134, v6, v7 offset0:40 offset1:172
	ds_write2_b32 v135, v8, v9 offset0:64 offset1:196
	ds_write2_b32 v136, v10, v11 offset0:72 offset1:204
	ds_write2_b32 v137, v12, v13 offset0:96 offset1:228
	ds_write2_b32 v138, v14, v15 offset0:104 offset1:236
	s_waitcnt lgkmcnt(0)
	s_barrier
	ds_read_b128 v[0:3], v56 offset:48
	ds_read_b128 v[4:7], v56 offset:32
	ds_read_b128 v[8:11], v56
	ds_read_b128 v[12:15], v56 offset:16
	s_waitcnt lgkmcnt(3)
	v_pk_mul_f32 v[18:19], v[0:1], v[0:1]
	s_waitcnt lgkmcnt(2)
	v_pk_mul_f32 v[44:45], v[4:5], v[4:5]
	s_waitcnt lgkmcnt(1)
	v_pk_mul_f32 v[72:73], v[8:9], v[8:9]
	v_pk_mul_f32 v[70:71], v[10:11], v[10:11]
	v_add_f32_e32 v65, v72, v73
	v_add_f32_e32 v65, v65, v70
	s_waitcnt lgkmcnt(0)
	v_pk_mul_f32 v[68:69], v[12:13], v[12:13]
	v_add_f32_e32 v65, v65, v71
	v_add_f32_e32 v65, v65, v68
	v_pk_mul_f32 v[66:67], v[14:15], v[14:15]
	v_add_f32_e32 v65, v65, v69
	v_add_f32_e32 v65, v65, v66
	v_add_f32_e32 v65, v65, v67
	v_add_f32_e32 v44, v65, v44
	v_pk_mul_f32 v[42:43], v[6:7], v[6:7]
	v_add_f32_e32 v44, v44, v45
	v_add_f32_e32 v42, v44, v42
	v_add_f32_e32 v42, v42, v43
	v_add_f32_e32 v18, v42, v18
	v_pk_mul_f32 v[16:17], v[2:3], v[2:3]
	v_add_f32_e32 v18, v18, v19
	v_add_f32_e32 v16, v18, v16
	v_add_f32_e32 v16, v16, v17
	ds_bpermute_b32 v17, v57, v16
	s_waitcnt lgkmcnt(0)
	v_add_f32_e32 v16, v16, v17
	ds_bpermute_b32 v17, v58, v16
	s_waitcnt lgkmcnt(0)
	v_add_f32_e32 v16, v16, v17
	ds_bpermute_b32 v17, v59, v16
	s_waitcnt lgkmcnt(0)
	v_add_f32_e32 v16, v16, v17
	v_fmamk_f32 v16, v16, 0x3c000000, v64
	v_mul_f32_e32 v17, 0x4b800000, v16
	v_cmp_gt_f32_e32 vcc, s53, v16
	s_nop 1
	v_cndmask_b32_e32 v16, v16, v17, vcc
	v_rsq_f32_e32 v16, v16
	s_nop 0
	v_mul_f32_e32 v17, 0x45800000, v16
	v_cndmask_b32_e32 v16, v16, v17, vcc
	v_pk_mul_f32 v[8:9], v[8:9], v[16:17] op_sel_hi:[1,0]
	v_pk_mul_f32 v[10:11], v[10:11], v[16:17] op_sel_hi:[1,0]
	v_pk_mul_f32 v[12:13], v[12:13], v[16:17] op_sel_hi:[1,0]
	v_pk_mul_f32 v[14:15], v[14:15], v[16:17] op_sel_hi:[1,0]
	v_pk_mul_f32 v[4:5], v[4:5], v[16:17] op_sel_hi:[1,0]
	v_pk_mul_f32 v[6:7], v[6:7], v[16:17] op_sel_hi:[1,0]
	v_pk_mul_f32 v[0:1], v[0:1], v[16:17] op_sel_hi:[1,0]
	v_pk_mul_f32 v[2:3], v[2:3], v[16:17] op_sel_hi:[1,0]
	v_pk_mul_f32 v[8:9], v[106:107], v[8:9]
	v_pk_mul_f32 v[10:11], v[108:109], v[10:11]
	v_pk_mul_f32 v[12:13], v[110:111], v[12:13]
	v_pk_mul_f32 v[14:15], v[112:113], v[14:15]
	v_pk_mul_f32 v[4:5], v[114:115], v[4:5]
	v_pk_mul_f32 v[6:7], v[116:117], v[6:7]
	v_pk_mul_f32 v[0:1], v[118:119], v[0:1]
	v_pk_mul_f32 v[2:3], v[120:121], v[2:3]
	v_pk_mul_f32 v[8:9], v[8:9], v[98:99]
	v_pk_mul_f32 v[10:11], v[10:11], v[126:127]
	v_pk_mul_f32 v[12:13], v[12:13], v[100:101]
	v_pk_mul_f32 v[14:15], v[14:15], v[124:125]
	v_pk_mul_f32 v[4:5], v[4:5], v[102:103]
	v_pk_mul_f32 v[6:7], v[6:7], v[122:123]
	v_pk_mul_f32 v[16:17], v[0:1], v[46:47]
	v_pk_mul_f32 v[18:19], v[2:3], v[128:129]
	v_cvt_pk_bf16_f32 v0, v8, v9
	v_cvt_pk_bf16_f32 v1, v10, v11
	v_cvt_pk_bf16_f32 v2, v12, v13
	v_cvt_pk_bf16_f32 v3, v14, v15
	v_cvt_pk_bf16_f32 v4, v4, v5
	v_cvt_pk_bf16_f32 v5, v6, v7
	v_cvt_pk_bf16_f32 v6, v16, v17
	v_cvt_pk_bf16_f32 v7, v18, v19
	flat_store_dwordx4 v[48:49], v[0:3]
	flat_store_dwordx4 v[48:49], v[4:7] offset:16
	s_waitcnt lgkmcnt(0)
	s_barrier
	s_cbranch_scc0 .LBB0_1312
	v_mov_b32_e32 v217, s11
	s_bitcmp1_b32 s94, 0
	s_cbranch_scc1 .Lattn_done

.LBB0_1595:
	v_readlane_b32 s96, v238, 5
	v_readlane_b32 s64, v239, 51
	v_readlane_b32 s2, v238, 48
	v_readlane_b32 s92, v238, 38
	v_readlane_b32 s94, v238, 40
	v_readlane_b32 s87, v238, 4
	v_readlane_b32 s97, v238, 6
	v_readlane_b32 s84, v238, 7
	v_readlane_b32 s65, v239, 52
	v_readlane_b32 s68, v239, 55
	v_readlane_b32 s69, v239, 56
	v_readlane_b32 s76, v239, 63
	v_readlane_b32 s77, v238, 0
	v_readlane_b32 s3, v238, 49
	v_readlane_b32 s93, v238, 39
	v_readlane_b32 s95, v238, 41
	v_readlane_b32 s66, v239, 53
	v_readlane_b32 s67, v239, 54
	v_readlane_b32 s70, v239, 57
	v_readlane_b32 s71, v239, 58
	v_readlane_b32 s72, v239, 59
	v_readlane_b32 s73, v239, 60
	v_readlane_b32 s74, v239, 61
	v_readlane_b32 s75, v239, 62
	v_readlane_b32 s78, v238, 1
	v_readlane_b32 s79, v238, 2
	s_bitcmp1_b32 s94, 0
	s_cbranch_scc0 .LBB0_1596
	s_lshl_b32 s10, s94, 1
	s_branch .LBB0_1310
